# s5 E@U: E slice staged through idle carry LDS tile with coalesced loads, A fragments from LDS
# speedup vs baseline: 1.0067x; 1.0067x over previous
.LBB0_719:
	v_lshrrev_b32_e32 v44, 6, v210
	v_bfe_u32 v45, v210, 5, 1
	v_and_b32_e32 v46, 31, v210
	v_lshlrev_b32_e32 v34, 13, v44
	v_lshl_add_u32 v34, v45, 9, v34
	v_sub_u32_e32 v47, v46, v45
	v_lshl_add_u32 v34, v47, 4, v34
	s_lshl_b32 s24, s88, 9
	v_add_u32_e32 v34, s24, v34
	v_add_u32_e32 v34, 0x1000, v34
	v_mov_b32_e32 v35, v33
	v_lshl_add_u64 v[34:35], v[150:151], 0, v[34:35]
	global_load_dwordx4 v[166:169], v[34:35], off offset:-4096
	global_load_dwordx4 v[170:173], v[34:35], off offset:-3072
	global_load_dwordx4 v[174:177], v[34:35], off offset:-2048
	global_load_dwordx4 v[190:193], v[34:35], off offset:-1024
	global_load_dwordx4 v[194:197], v[34:35], off offset:0
	global_load_dwordx4 v[198:201], v[34:35], off offset:1024
	global_load_dwordx4 v[202:205], v[34:35], off offset:2048
	global_load_dwordx4 v[206:209], v[34:35], off offset:3072
	v_lshl_add_u32 v44, v44, 4, v45
	v_mul_u32_u24_e32 v44, 0x210, v44
	v_lshl_add_u32 v44, v46, 4, v44
	v_add_u32_e32 v44, 0x10800, v44
	v_mul_u32_u24_e32 v47, 0x210, v119
	v_lshl_add_u32 v45, v45, 4, v47
	v_add_u32_e32 v45, 0x10800, v45
	v_add_u32_e32 v32, v139, v141
	ds_read_b128 v[246:249], v32
	ds_read_b128 v[250:253], v32 offset:16896
	ds_read_b128 v[36:39], v32 offset:32
	ds_read_b128 v[40:43], v32 offset:16928
	s_waitcnt vmcnt(7)
	ds_write_b128 v44, v[166:169]
	s_waitcnt vmcnt(6)
	ds_write_b128 v44, v[170:173] offset:1056
	s_waitcnt vmcnt(5)
	ds_write_b128 v44, v[174:177] offset:2112
	s_waitcnt vmcnt(4)
	ds_write_b128 v44, v[190:193] offset:3168
	s_waitcnt vmcnt(3)
	ds_write_b128 v44, v[194:197] offset:4224
	s_waitcnt vmcnt(2)
	ds_write_b128 v44, v[198:201] offset:5280
	s_waitcnt vmcnt(1)
	ds_write_b128 v44, v[202:205] offset:6336
	s_waitcnt vmcnt(0)
	ds_write_b128 v44, v[206:209] offset:7392
	s_waitcnt lgkmcnt(0)
	s_barrier
	ds_read_b128 v[234:237], v45
	ds_read_b128 v[238:241], v45 offset:32
	ds_read_b128 v[242:245], v45 offset:64
	s_waitcnt lgkmcnt(2)
	v_mfma_f32_32x32x16_bf16 v[96:111], v[234:237], v[246:249], 0
	ds_read_b128 v[246:249], v32 offset:64
	s_waitcnt lgkmcnt(3)
	v_mfma_f32_32x32x16_bf16 v[80:95], v[234:237], v[250:253], 0
	ds_read_b128 v[250:253], v32 offset:16960
	ds_read_b128 v[234:237], v45 offset:96
	s_waitcnt lgkmcnt(4)
	v_mfma_f32_32x32x16_bf16 v[96:111], v[238:241], v[36:39], v[96:111]
	ds_read_b128 v[36:39], v32 offset:96
	s_waitcnt lgkmcnt(5)
	v_mfma_f32_32x32x16_bf16 v[80:95], v[238:241], v[40:43], v[80:95]
	ds_read_b128 v[40:43], v32 offset:16992
	ds_read_b128 v[238:241], v45 offset:128
	s_waitcnt lgkmcnt(5)
	v_mfma_f32_32x32x16_bf16 v[96:111], v[242:245], v[246:249], v[96:111]
	ds_read_b128 v[246:249], v32 offset:128
	s_waitcnt lgkmcnt(5)
	v_mfma_f32_32x32x16_bf16 v[80:95], v[242:245], v[250:253], v[80:95]
	ds_read_b128 v[250:253], v32 offset:17024
	ds_read_b128 v[242:245], v45 offset:160
	s_waitcnt lgkmcnt(5)
	v_mfma_f32_32x32x16_bf16 v[96:111], v[234:237], v[36:39], v[96:111]
	ds_read_b128 v[36:39], v32 offset:160
	s_waitcnt lgkmcnt(5)
	v_mfma_f32_32x32x16_bf16 v[80:95], v[234:237], v[40:43], v[80:95]
	ds_read_b128 v[40:43], v32 offset:17056
	ds_read_b128 v[234:237], v45 offset:192
	s_waitcnt lgkmcnt(5)
	v_mfma_f32_32x32x16_bf16 v[96:111], v[238:241], v[246:249], v[96:111]
	ds_read_b128 v[246:249], v32 offset:192
	s_waitcnt lgkmcnt(5)
	v_mfma_f32_32x32x16_bf16 v[80:95], v[238:241], v[250:253], v[80:95]
	ds_read_b128 v[250:253], v32 offset:17088
	ds_read_b128 v[238:241], v45 offset:224
	s_waitcnt lgkmcnt(5)
	v_mfma_f32_32x32x16_bf16 v[96:111], v[242:245], v[36:39], v[96:111]
	ds_read_b128 v[36:39], v32 offset:224
	s_waitcnt lgkmcnt(5)
	v_mfma_f32_32x32x16_bf16 v[80:95], v[242:245], v[40:43], v[80:95]
	ds_read_b128 v[40:43], v32 offset:17120
	ds_read_b128 v[242:245], v45 offset:256
	s_waitcnt lgkmcnt(5)
	v_mfma_f32_32x32x16_bf16 v[96:111], v[234:237], v[246:249], v[96:111]
	ds_read_b128 v[246:249], v32 offset:256
	s_waitcnt lgkmcnt(5)
	v_mfma_f32_32x32x16_bf16 v[80:95], v[234:237], v[250:253], v[80:95]
	ds_read_b128 v[250:253], v32 offset:17152
	ds_read_b128 v[234:237], v45 offset:288
	s_waitcnt lgkmcnt(5)
	v_mfma_f32_32x32x16_bf16 v[96:111], v[238:241], v[36:39], v[96:111]
	ds_read_b128 v[36:39], v32 offset:288
	s_waitcnt lgkmcnt(5)
	v_mfma_f32_32x32x16_bf16 v[80:95], v[238:241], v[40:43], v[80:95]
	ds_read_b128 v[40:43], v32 offset:17184
	ds_read_b128 v[238:241], v45 offset:320
	s_waitcnt lgkmcnt(5)
	v_mfma_f32_32x32x16_bf16 v[96:111], v[242:245], v[246:249], v[96:111]
	ds_read_b128 v[246:249], v32 offset:320
	s_waitcnt lgkmcnt(5)
	v_mfma_f32_32x32x16_bf16 v[80:95], v[242:245], v[250:253], v[80:95]
	ds_read_b128 v[250:253], v32 offset:17216
	ds_read_b128 v[242:245], v45 offset:352
	s_waitcnt lgkmcnt(5)
	v_mfma_f32_32x32x16_bf16 v[96:111], v[234:237], v[36:39], v[96:111]
	ds_read_b128 v[36:39], v32 offset:352
	s_waitcnt lgkmcnt(5)
	v_mfma_f32_32x32x16_bf16 v[80:95], v[234:237], v[40:43], v[80:95]
	ds_read_b128 v[40:43], v32 offset:17248
	ds_read_b128 v[234:237], v45 offset:384
	s_waitcnt lgkmcnt(5)
	v_mfma_f32_32x32x16_bf16 v[96:111], v[238:241], v[246:249], v[96:111]
	ds_read_b128 v[246:249], v32 offset:384
	s_waitcnt lgkmcnt(5)
	v_mfma_f32_32x32x16_bf16 v[80:95], v[238:241], v[250:253], v[80:95]
	ds_read_b128 v[250:253], v32 offset:17280
	ds_read_b128 v[238:241], v45 offset:416
	s_waitcnt lgkmcnt(5)
	v_mfma_f32_32x32x16_bf16 v[96:111], v[242:245], v[36:39], v[96:111]
	ds_read_b128 v[36:39], v32 offset:416
	s_waitcnt lgkmcnt(5)
	v_mfma_f32_32x32x16_bf16 v[80:95], v[242:245], v[40:43], v[80:95]
	ds_read_b128 v[40:43], v32 offset:17312
	ds_read_b128 v[242:245], v45 offset:448
	s_waitcnt lgkmcnt(5)
	v_mfma_f32_32x32x16_bf16 v[96:111], v[234:237], v[246:249], v[96:111]
	ds_read_b128 v[246:249], v32 offset:448
	s_waitcnt lgkmcnt(5)
	v_mfma_f32_32x32x16_bf16 v[80:95], v[234:237], v[250:253], v[80:95]
	ds_read_b128 v[250:253], v32 offset:17344
	ds_read_b128 v[234:237], v45 offset:480
	s_waitcnt lgkmcnt(5)
	v_mfma_f32_32x32x16_bf16 v[96:111], v[238:241], v[36:39], v[96:111]
	ds_read_b128 v[36:39], v32 offset:480
	s_waitcnt lgkmcnt(5)
	v_mfma_f32_32x32x16_bf16 v[80:95], v[238:241], v[40:43], v[80:95]
	ds_read_b128 v[40:43], v32 offset:17376
	s_waitcnt lgkmcnt(4)
	v_mfma_f32_32x32x16_bf16 v[96:111], v[242:245], v[246:249], v[96:111]
	s_waitcnt lgkmcnt(3)
	v_mfma_f32_32x32x16_bf16 v[80:95], v[242:245], v[250:253], v[80:95]
	s_waitcnt lgkmcnt(1)
	v_mfma_f32_32x32x16_bf16 v[96:111], v[234:237], v[36:39], v[96:111]
	s_waitcnt lgkmcnt(0)
	v_mfma_f32_32x32x16_bf16 v[80:95], v[234:237], v[40:43], v[80:95]
	s_barrier
	s_nop 15
	ds_write_b128 v165, v[96:99]
	ds_write_b128 v165, v[100:103] offset:32
	ds_write_b128 v165, v[104:107] offset:64
	ds_write_b128 v165, v[108:111] offset:96
	ds_write_b128 v165, v[80:83] offset:16896
	ds_write_b128 v165, v[84:87] offset:16928
	ds_write_b128 v165, v[88:91] offset:16960
	ds_write_b128 v165, v[92:95] offset:16992
	s_waitcnt lgkmcnt(0)
	s_barrier
	s_and_b64 s[30:31], s[10:11], exec
	s_cbranch_scc0 .Ls5_nopf
	global_load_dwordx4 v[100:103], v[148:149], off
	global_load_dwordx4 v[104:107], v[148:149], off offset:32
	global_load_dwordx4 v[108:111], v[148:149], off offset:64
	global_load_dwordx4 v[166:169], v[148:149], off offset:96
	global_load_dwordx4 v[170:173], v[148:149], off offset:128
	global_load_dwordx4 v[174:177], v[148:149], off offset:160
	global_load_dwordx4 v[190:193], v[148:149], off offset:192
	global_load_dwordx4 v[194:197], v[148:149], off offset:224
	global_load_dwordx4 v[198:201], v[148:149], off offset:256
	global_load_dwordx4 v[202:205], v[148:149], off offset:288
	global_load_dwordx4 v[206:209], v[148:149], off offset:320
	global_load_dwordx4 v[234:237], v[148:149], off offset:352
	global_load_dwordx4 v[238:241], v[148:149], off offset:384
	global_load_dwordx4 v[242:245], v[148:149], off offset:416
	global_load_dwordx4 v[246:249], v[148:149], off offset:448
	global_load_dwordx4 v[250:253], v[148:149], off offset:480
